# scan: no transposed K copy (ds_read_b64_tr_b16 from sKt with the dual-use swizzle), state kept undecayed with the decay deferred to the next step, kt instead of kh; plus rows0 gain preload
# speedup vs baseline: 1.0285x; 1.0057x over previous
.LBB0_1144:
	s_ashr_i32 s5, s85, 2
	s_lshl_b32 s7, s85, 6
	s_lshl_b32 s6, s5, 8
	s_and_b32 s10, s7, 0x80
	s_or_b32 s6, s6, s10
	s_and_b32 s4, s85, 1
	s_bfe_i32 s8, s85, 0x10000
	s_ashr_i32 s12, s85, 4
	s_mul_hi_i32 s7, s6, 0x4200
	s_mulk_i32 s6, 0x4200
	s_and_b32 s11, s5, 3
	s_add_u32 s6, s56, s6
	s_addc_u32 s7, s57, s7
	s_cmp_eq_u32 s4, 0
	s_cselect_b64 s[4:5], -1, 0
	v_mov_b32_e32 v3, v148
	s_and_b64 s[14:15], s[4:5], exec
	s_mov_b32 s9, 0xc400000
	s_barrier
	s_cselect_b32 s9, s9, 0x10600000
	v_ashrrev_i32_e32 v14, 6, v3
	s_mov_b32 s13, 0x14800000
	v_add_u32_e32 v0, -4, v14
	s_cselect_b32 s13, s13, 0x1c800000
	s_cselect_b32 s86, 63, 0
	s_add_u32 s70, s54, s9
	v_lshrrev_b32_e32 v15, 1, v0
	v_and_b32_e32 v16, 1, v14
	s_addc_u32 s71, s55, 0
	v_cmp_gt_u32_e32 vcc, v16, v15
	s_add_u32 s13, s54, s13
	s_addc_u32 s14, s55, 0
	v_cndmask_b32_e64 v0, 0, 1, vcc
	v_cmp_lt_u32_e32 vcc, v16, v15
	s_lshl_b32 s87, s12, 8
	s_and_b32 s8, s8, 0xc0
	v_cndmask_b32_e64 v4, 0, 1, vcc
	s_add_i32 s87, s87, 0x10000
	v_cndmask_b32_e64 v17, v4, v0, s[4:5]
	s_or_b32 s15, s87, s8
	v_lshlrev_b32_e32 v4, 2, v3
	s_lshl_b32 s16, s8, 1
	s_or_b32 s8, s15, s86
	v_ashrrev_i32_e32 v149, 4, v3
	v_lshlrev_b32_e32 v0, 3, v3
	v_and_b32_e32 v21, 4, v4
	s_ashr_i32 s9, s8, 31
	v_and_or_b32 v22, v0, s51, v21
	v_add_u32_e32 v4, s15, v149
	v_ashrrev_i32_e32 v5, 31, v4
	v_lshl_or_b32 v136, s11, 7, v22
	s_lshl_b64 s[8:9], s[8:9], 10
	v_lshlrev_b64 v[4:5], 10, v[4:5]
	s_waitcnt vmcnt(11)
	v_lshlrev_b32_e32 v8, 1, v136
	s_add_u32 s8, s70, s8
	v_or_b32_e32 v4, v4, v8
	s_addc_u32 s9, s71, s9
	s_lshl_b32 s17, s11, 8
	v_add_u32_e32 v23, 0x200, v3
	s_waitcnt vmcnt(5)
	v_lshl_add_u64 v[6:7], s[76:77], 0, v[4:5]
	s_add_u32 s8, s8, s17
	v_ashrrev_i32_e32 v172, 4, v23
	s_addc_u32 s9, s9, 0
	v_lshlrev_b32_e32 v0, 1, v22
	global_load_dwordx2 v[138:139], v[6:7], off
	global_load_dwordx2 v[140:141], v[6:7], off offset:16
	global_load_dwordx2 v[142:143], v0, s[8:9]
	global_load_dwordx2 v[144:145], v0, s[8:9] offset:16
	v_add_u32_e32 v6, s15, v172
	v_ashrrev_i32_e32 v7, 31, v6
	v_lshlrev_b64 v[6:7], 10, v[6:7]
	v_lshl_add_u64 v[4:5], s[70:71], 0, v[4:5]
	v_or_b32_e32 v6, v6, v8
	v_lshl_add_u64 v[8:9], s[76:77], 0, v[6:7]
	global_load_dwordx2 v[156:157], v[4:5], off
	global_load_dwordx2 v[158:159], v[4:5], off offset:16
	global_load_dwordx2 v[160:161], v[8:9], off
	global_load_dwordx2 v[162:163], v[8:9], off offset:16
	v_lshl_add_u64 v[4:5], s[70:71], 0, v[6:7]
	global_load_dwordx2 v[164:165], v[4:5], off
	global_load_dwordx2 v[166:167], v[4:5], off offset:16
	v_ashrrev_i32_e32 v12, 3, v3
	v_mov_b64_e32 v[4:5], s[6:7]
	v_mad_i64_i32 v[6:7], s[6:7], v12, s33, v[4:5]
	v_add_u32_e32 v12, 64, v12
	s_or_b32 s48, s16, 0x4000
	v_lshlrev_b32_e32 v24, 4, v3
	v_mad_i64_i32 v[4:5], s[6:7], v12, s33, v[4:5]
	v_lshl_add_u64 v[8:9], v[6:7], 0, s[48:49]
	v_and_b32_e32 v10, 0x70, v24
	v_mov_b32_e32 v11, v1
	v_lshl_add_u64 v[12:13], v[4:5], 0, s[48:49]
	v_lshl_add_u64 v[8:9], v[8:9], 0, v[10:11]
	v_lshl_add_u64 v[12:13], v[12:13], 0, v[10:11]
	global_load_dwordx4 v[128:131], v[8:9], off
	global_load_dwordx4 v[132:135], v[12:13], off
	v_ashrrev_i32_e32 v8, 7, v3
	v_lshlrev_b32_e32 v9, 1, v149
	v_lshrrev_b32_e32 v12, 1, v21
	v_and_b32_e32 v25, 14, v9
	v_lshlrev_b32_e32 v9, 7, v22
	v_xor_b32_e32 v13, v12, v8
	v_lshl_add_u32 v26, v13, 4, v9
	v_or_b32_e32 v13, 2, v22
	v_or_b32_e32 v29, 3, v22
	v_or_b32_e32 v32, 8, v22
	v_or_b32_e32 v35, 9, v22
	v_or_b32_e32 v38, 10, v22
	v_or_b32_e32 v22, 11, v22
	v_lshlrev_b32_e32 v27, 7, v13
	v_lshrrev_b32_e32 v13, 1, v13
	v_lshlrev_b32_e32 v30, 7, v29
	v_lshrrev_b32_e32 v29, 1, v29
	v_lshlrev_b32_e32 v33, 7, v32
	v_lshrrev_b32_e32 v32, 1, v32
	v_lshlrev_b32_e32 v36, 7, v35
	v_lshrrev_b32_e32 v35, 1, v35
	v_lshlrev_b32_e32 v39, 7, v38
	v_lshrrev_b32_e32 v38, 1, v38
	v_lshlrev_b32_e32 v41, 7, v22
	v_lshrrev_b32_e32 v22, 1, v22
	v_bitop3_b32 v28, v13, v8, 3 bitop3:0x6c
	v_bitop3_b32 v31, v29, v8, 3 bitop3:0x6c
	v_bitop3_b32 v34, v32, v8, 6 bitop3:0x6c
	v_bitop3_b32 v37, v35, v8, 6 bitop3:0x6c
	v_bitop3_b32 v40, v38, v8, 7 bitop3:0x6c
	v_bitop3_b32 v8, v22, v8, 7 bitop3:0x6c
	v_xor_b32_e32 v43, v149, v3
	v_lshl_add_u32 v42, v8, 4, v41
	v_lshlrev_b32_e32 v8, 8, v149
	v_lshlrev_b32_e32 v43, 4, v43
	s_add_u32 s8, s70, s17
	v_and_or_b32 v173, v43, s84, v8
	v_ashrrev_i32_e32 v8, 7, v23
	s_addc_u32 s9, s71, 0
	v_lshl_add_u64 v[154:155], v[4:5], 0, v[10:11]
	s_lshl_b32 s88, s12, 13
	v_lshlrev_b32_e32 v4, 5, v3
	v_lshlrev_b32_e32 v5, 2, v21
	s_movk_i32 s12, 0xffc0
	v_xor_b32_e32 v12, v12, v8
	v_and_or_b32 v4, v4, s12, v5
	v_lshl_add_u32 v43, v12, 4, v9
	v_bitop3_b32 v9, v13, v8, 3 bitop3:0x6c
	v_add_u32_e32 v176, 0x16000, v4
	v_and_b32_e32 v4, 1, v17
	v_lshl_add_u32 v28, v28, 4, v27
	v_lshl_add_u32 v27, v9, 4, v27
	v_bitop3_b32 v9, v29, v8, 3 bitop3:0x6c
	v_cmp_eq_u32_e32 vcc, 1, v4
	v_lshl_add_u32 v29, v9, 4, v30
	v_bitop3_b32 v9, v32, v8, 6 bitop3:0x6c
	s_xor_b64 s[78:79], vcc, -1
	s_lshl_b32 s11, s11, 9
	v_lshl_add_u32 v31, v31, 4, v30
	v_lshl_add_u32 v30, v9, 4, v33
	v_bitop3_b32 v9, v35, v8, 6 bitop3:0x6c
	s_add_u32 s11, s13, s11
	v_and_b32_e32 v18, 31, v3
	v_lshl_add_u32 v32, v9, 4, v36
	v_bitop3_b32 v9, v38, v8, 7 bitop3:0x6c
	v_lshl_add_u64 v[146:147], s[8:9], 0, v[0:1]
	v_lshlrev_b32_e32 v0, 5, v14
	s_addc_u32 s12, s14, 0
	s_lshl_b32 s10, s10, 1
	v_lshrrev_b32_e32 v2, 5, v3
	v_bfe_u32 v19, v3, 5, 1
	v_bfe_u32 v20, v3, 1, 3
	v_lshl_add_u32 v34, v34, 4, v33
	v_lshl_add_u32 v33, v9, 4, v39
	v_xor_b32_e32 v9, v172, v3
	v_and_b32_e32 v35, 0xffffff80, v24
	v_bitop3_b32 v24, v24, s51, v3 bitop3:0x48
	v_cmp_gt_i32_e64 s[6:7], 16, v3
	v_lshl_add_u64 v[152:153], v[6:7], 0, v[10:11]
	v_and_b32_e32 v0, 0x60, v0
	v_lshlrev_b32_e32 v177, 8, v18
	v_and_b32_e32 v6, 15, v3
	v_lshlrev_b32_e32 v3, 1, v3
	s_add_u32 s10, s11, s10
	v_lshl_or_b32 v179, v16, 13, v177
	v_lshl_or_b32 v7, v16, 5, v18
	v_and_b32_e32 v16, 14, v3
	v_or_b32_e32 v3, v0, v18
	s_addc_u32 s11, s12, 0
	v_lshlrev_b32_e32 v0, 1, v0
	v_lshl_add_u64 v[4:5], s[10:11], 0, v[0:1]
	v_lshlrev_b32_e32 v0, 1, v18
	v_lshl_add_u64 v[4:5], v[4:5], 0, v[0:1]
	v_bitop3_b32 v0, v2, v6, 1 bitop3:0x6c
	v_lshlrev_b32_e32 v184, 4, v0
	v_bitop3_b32 v0, v19, v6, 2 bitop3:0x36
	v_lshlrev_b32_e32 v185, 4, v0
	v_bitop3_b32 v0, v19, v6, 4 bitop3:0x36
	v_lshlrev_b32_e32 v186, 4, v0
	v_bitop3_b32 v0, v19, v6, 6 bitop3:0x36
	v_lshlrev_b32_e32 v187, 4, v0
	v_bitop3_b32 v0, v19, v6, 8 bitop3:0x36
	v_bitop3_b32 v8, v22, v8, 7 bitop3:0x6c
	v_lshlrev_b32_e32 v188, 4, v0
	v_bitop3_b32 v0, v19, v6, 10 bitop3:0x36
	v_lshl_add_u32 v22, v8, 4, v41
	v_lshlrev_b32_e32 v8, 8, v172
	v_lshlrev_b32_e32 v9, 4, v9
	v_lshlrev_b32_e32 v189, 4, v0
	v_bitop3_b32 v0, v19, v6, 12 bitop3:0x36
	v_and_or_b32 v174, v9, s84, v8
	v_lshlrev_b32_e32 v8, 2, v19
	v_lshlrev_b32_e32 v190, 4, v0
	v_bitop3_b32 v0, v19, v6, 14 bitop3:0x36
	v_lshlrev_b32_e32 v191, 4, v0
	v_lshl_or_b32 v0, v15, 5, v8
	v_cmp_le_u32_e32 vcc, v7, v0
	v_lshlrev_b32_e32 v180, 7, v3
	v_lshrrev_b32_e32 v9, 3, v7
	v_cndmask_b32_e64 v3, 0, 1, vcc
	v_cmp_ge_u32_e32 vcc, v7, v0
	v_lshlrev_b32_e32 v8, 4, v9
	v_lshlrev_b32_e32 v181, 7, v18
	v_cndmask_b32_e64 v6, 0, 1, vcc
	v_cndmask_b32_e64 v3, v6, v3, s[4:5]
	v_and_b32_e32 v3, 1, v3
	v_cmp_eq_u32_e64 s[10:11], 1, v3
	v_lshlrev_b32_e32 v3, 7, v0
	v_lshlrev_b32_e32 v6, 5, v19
	v_bitop3_b32 v3, v3, v8, v6 bitop3:0xf6
	v_add_u32_e32 v17, 0x14000, v3
	v_or_b32_e32 v3, 1, v0
	v_cmp_gt_u32_e32 vcc, v7, v0
	v_lshl_add_u32 v37, v37, 4, v36
	v_lshl_add_u32 v40, v40, 4, v39
	v_cndmask_b32_e64 v10, 0, 1, vcc
	v_cmp_le_u32_e32 vcc, v7, v3
	v_lshlrev_b32_e32 v3, 7, v3
	v_bitop3_b32 v3, v3, v8, v6 bitop3:0xf6
	v_cndmask_b32_e64 v11, 0, 1, vcc
	v_cndmask_b32_e64 v10, v10, v11, s[4:5]
	v_add_u32_e32 v18, 0x14000, v3
	v_or_b32_e32 v3, 2, v0
	v_and_b32_e32 v10, 1, v10
	v_cmp_le_u32_e32 vcc, v7, v3
	v_cmp_eq_u32_e64 s[12:13], 1, v10
	v_lshlrev_b32_e32 v23, 1, v172
	v_cndmask_b32_e64 v10, 0, 1, vcc
	v_cmp_ge_u32_e32 vcc, v7, v3
	v_and_b32_e32 v23, 14, v23
	v_cmp_gt_i32_e64 s[8:9], 4, v14
	v_cndmask_b32_e64 v11, 0, 1, vcc
	v_cndmask_b32_e64 v10, v11, v10, s[4:5]
	v_and_b32_e32 v10, 1, v10
	v_cmp_eq_u32_e64 s[14:15], 1, v10
	v_lshrrev_b32_e32 v10, 1, v3
	v_bitop3_b32 v10, v10, v9, 3 bitop3:0x6c
	v_lshlrev_b32_e32 v10, 4, v10
	v_lshl_or_b32 v3, v3, 7, v10
	v_add_u32_e32 v21, 0x14000, v3
	v_or_b32_e32 v3, 3, v0
	v_cmp_le_u32_e32 vcc, v7, v3
	v_lshl_or_b32 v178, v15, 13, v177
	v_mov_b32_e32 v14, v1
	v_cndmask_b32_e64 v10, 0, 1, vcc
	v_cmp_ge_u32_e32 vcc, v7, v3
	v_mov_b32_e32 v15, v1
	v_lshl_or_b32 v183, v19, 4, v137
	v_cndmask_b32_e64 v11, 0, 1, vcc
	v_cndmask_b32_e64 v10, v11, v10, s[4:5]
	v_and_b32_e32 v10, 1, v10
	v_cmp_eq_u32_e64 s[16:17], 1, v10
	v_lshrrev_b32_e32 v10, 1, v3
	v_bitop3_b32 v10, v10, v9, 3 bitop3:0x6c
	v_lshlrev_b32_e32 v10, 4, v10
	v_lshl_or_b32 v3, v3, 7, v10
	v_add_u32_e32 v36, 0x14000, v3
	v_or_b32_e32 v3, 8, v0
	v_cmp_le_u32_e32 vcc, v7, v3
	v_mov_b32_e32 v12, v1
	v_mov_b32_e32 v13, v1
	v_cndmask_b32_e64 v10, 0, 1, vcc
	v_cmp_ge_u32_e32 vcc, v7, v3
	v_add_u32_e32 v197, v26, v25
	v_add_u32_e32 v198, v28, v25
	v_cndmask_b32_e64 v11, 0, 1, vcc
	v_cndmask_b32_e64 v10, v11, v10, s[4:5]
	v_and_b32_e32 v10, 1, v10
	v_cmp_eq_u32_e64 s[18:19], 1, v10
	v_lshrrev_b32_e32 v10, 1, v3
	v_bitop3_b32 v10, v10, v9, 6 bitop3:0x6c
	v_lshlrev_b32_e32 v10, 4, v10
	v_lshl_or_b32 v3, v3, 7, v10
	v_add_u32_e32 v38, 0x14000, v3
	v_or_b32_e32 v3, 9, v0
	v_cmp_le_u32_e32 vcc, v7, v3
	v_add_u32_e32 v199, v31, v25
	v_add_u32_e32 v200, v34, v25
	v_cndmask_b32_e64 v10, 0, 1, vcc
	v_cmp_ge_u32_e32 vcc, v7, v3
	v_add_u32_e32 v201, v37, v25
	v_add_u32_e32 v202, v40, v25
	v_cndmask_b32_e64 v11, 0, 1, vcc
	v_cndmask_b32_e64 v10, v11, v10, s[4:5]
	v_and_b32_e32 v10, 1, v10
	v_cmp_eq_u32_e64 s[20:21], 1, v10
	v_lshrrev_b32_e32 v10, 1, v3
	v_bitop3_b32 v10, v10, v9, 6 bitop3:0x6c
	v_lshlrev_b32_e32 v10, 4, v10
	v_lshl_or_b32 v3, v3, 7, v10
	v_add_u32_e32 v39, 0x14000, v3
	v_or_b32_e32 v3, 10, v0
	v_cmp_le_u32_e32 vcc, v7, v3
	v_add_u32_e32 v203, v42, v25
	v_add_u32_e32 v204, v43, v23
	v_cndmask_b32_e64 v10, 0, 1, vcc
	v_cmp_ge_u32_e32 vcc, v7, v3
	v_add_u32_e32 v205, v27, v23
	v_add_u32_e32 v206, v29, v23
	v_cndmask_b32_e64 v11, 0, 1, vcc
	v_cndmask_b32_e64 v10, v11, v10, s[4:5]
	v_and_b32_e32 v10, 1, v10
	v_cmp_eq_u32_e64 s[22:23], 1, v10
	v_lshrrev_b32_e32 v10, 1, v3
	v_bitop3_b32 v10, v10, v9, 7 bitop3:0x6c
	v_lshlrev_b32_e32 v10, 4, v10
	v_lshl_or_b32 v3, v3, 7, v10
	v_add_u32_e32 v41, 0x14000, v3
	v_or_b32_e32 v3, 11, v0
	v_cmp_le_u32_e32 vcc, v7, v3
	v_add_u32_e32 v207, v30, v23
	v_add_u32_e32 v208, v32, v23
	v_cndmask_b32_e64 v10, 0, 1, vcc
	v_cmp_ge_u32_e32 vcc, v7, v3
	v_add_u32_e32 v209, v33, v23
	v_add_u32_e32 v210, v22, v23
	v_cndmask_b32_e64 v11, 0, 1, vcc
	v_cndmask_b32_e64 v10, v11, v10, s[4:5]
	v_and_b32_e32 v10, 1, v10
	v_cmp_eq_u32_e64 s[24:25], 1, v10
	v_lshrrev_b32_e32 v10, 1, v3
	v_bitop3_b32 v10, v10, v9, 7 bitop3:0x6c
	v_lshlrev_b32_e32 v10, 4, v10
	v_lshl_or_b32 v3, v3, 7, v10
	v_add_u32_e32 v44, 0x14000, v3
	v_or_b32_e32 v3, 16, v0
	v_cmp_le_u32_e32 vcc, v7, v3
	v_add_u32_e32 v211, v35, v24
	v_add_u32_e32 v212, v17, v16
	v_cndmask_b32_e64 v10, 0, 1, vcc
	v_cmp_ge_u32_e32 vcc, v7, v3
	v_lshlrev_b32_e32 v3, 7, v3
	v_bitop3_b32 v3, v3, v8, v6 bitop3:0xf6
	v_cndmask_b32_e64 v11, 0, 1, vcc
	v_cndmask_b32_e64 v10, v11, v10, s[4:5]
	v_add_u32_e32 v45, 0x14000, v3
	v_or_b32_e32 v3, 17, v0
	v_and_b32_e32 v10, 1, v10
	v_cmp_le_u32_e32 vcc, v7, v3
	v_cmp_eq_u32_e64 s[26:27], 1, v10
	v_add_u32_e32 v213, v18, v16
	v_cndmask_b32_e64 v10, 0, 1, vcc
	v_cmp_ge_u32_e32 vcc, v7, v3
	v_lshlrev_b32_e32 v3, 7, v3
	v_bitop3_b32 v3, v3, v8, v6 bitop3:0xf6
	v_add_u32_e32 v46, 0x14000, v3
	v_or_b32_e32 v3, 18, v0
	v_cndmask_b32_e64 v11, 0, 1, vcc
	v_cmp_le_u32_e32 vcc, v7, v3
	v_cndmask_b32_e64 v10, v11, v10, s[4:5]
	v_and_b32_e32 v10, 1, v10
	v_cndmask_b32_e64 v6, 0, 1, vcc
	v_cmp_ge_u32_e32 vcc, v7, v3
	v_cmp_eq_u32_e64 s[28:29], 1, v10
	v_mov_b32_e32 v10, v1
	v_cndmask_b32_e64 v8, 0, 1, vcc
	v_cndmask_b32_e64 v6, v8, v6, s[4:5]
	v_and_b32_e32 v6, 1, v6
	v_cmp_eq_u32_e64 s[30:31], 1, v6
	v_lshrrev_b32_e32 v6, 1, v3
	v_bitop3_b32 v6, v6, v9, 3 bitop3:0x6c
	v_lshlrev_b32_e32 v6, 4, v6
	v_lshl_or_b32 v3, v3, 7, v6
	v_add_u32_e32 v47, 0x14000, v3
	v_or_b32_e32 v3, 19, v0
	v_cmp_le_u32_e32 vcc, v7, v3
	v_mov_b32_e32 v11, v1
	v_add_u32_e32 v214, v21, v16
	v_cndmask_b32_e64 v6, 0, 1, vcc
	v_cmp_ge_u32_e32 vcc, v7, v3
	v_add_u32_e32 v215, v36, v16
	v_add_u32_e32 v216, v38, v16
	v_cndmask_b32_e64 v8, 0, 1, vcc
	v_cndmask_b32_e64 v6, v8, v6, s[4:5]
	v_and_b32_e32 v6, 1, v6
	v_cmp_eq_u32_e64 s[34:35], 1, v6
	v_lshrrev_b32_e32 v6, 1, v3
	v_bitop3_b32 v6, v6, v9, 3 bitop3:0x6c
	v_lshlrev_b32_e32 v6, 4, v6
	v_lshl_or_b32 v3, v3, 7, v6
	v_add_u32_e32 v48, 0x14000, v3
	v_or_b32_e32 v3, 24, v0
	v_cmp_le_u32_e32 vcc, v7, v3
	v_add_u32_e32 v217, v39, v16
	v_add_u32_e32 v218, v41, v16
	v_cndmask_b32_e64 v6, 0, 1, vcc
	v_cmp_ge_u32_e32 vcc, v7, v3
	v_add_u32_e32 v219, v44, v16
	v_add_u32_e32 v220, v45, v16
	v_cndmask_b32_e64 v8, 0, 1, vcc
	v_cndmask_b32_e64 v6, v8, v6, s[4:5]
	v_and_b32_e32 v6, 1, v6
	v_cmp_eq_u32_e64 s[36:37], 1, v6
	v_lshrrev_b32_e32 v6, 1, v3
	v_bitop3_b32 v6, v6, v9, 6 bitop3:0x6c
	v_lshlrev_b32_e32 v6, 4, v6
	v_lshl_or_b32 v3, v3, 7, v6
	v_add_u32_e32 v49, 0x14000, v3
	v_or_b32_e32 v3, 25, v0
	v_cmp_le_u32_e32 vcc, v7, v3
	v_add_u32_e32 v221, v46, v16
	v_add_u32_e32 v222, v47, v16
	v_cndmask_b32_e64 v6, 0, 1, vcc
	v_cmp_ge_u32_e32 vcc, v7, v3
	v_add_u32_e32 v223, v48, v16
	v_add_u32_e32 v224, v49, v16
	v_cndmask_b32_e64 v8, 0, 1, vcc
	v_cndmask_b32_e64 v6, v8, v6, s[4:5]
	v_and_b32_e32 v6, 1, v6
	v_cmp_eq_u32_e64 s[38:39], 1, v6
	v_lshrrev_b32_e32 v6, 1, v3
	v_bitop3_b32 v6, v6, v9, 6 bitop3:0x6c
	v_lshlrev_b32_e32 v6, 4, v6
	v_lshl_or_b32 v3, v3, 7, v6
	v_add_u32_e32 v50, 0x14000, v3
	v_or_b32_e32 v3, 26, v0
	v_cmp_le_u32_e32 vcc, v7, v3
	v_or_b32_e32 v0, 27, v0
	v_add_u32_e32 v225, v50, v16
	v_cndmask_b32_e64 v6, 0, 1, vcc
	v_cmp_ge_u32_e32 vcc, v7, v3
	v_or_b32_e32 v182, 0x14000, v181
	s_waitcnt vmcnt(16)
	v_mov_b64_e32 v[170:171], 0
	v_cndmask_b32_e64 v8, 0, 1, vcc
	v_cndmask_b32_e64 v6, v8, v6, s[4:5]
	v_and_b32_e32 v6, 1, v6
	v_cmp_eq_u32_e64 s[40:41], 1, v6
	v_lshrrev_b32_e32 v6, 1, v3
	v_bitop3_b32 v6, v6, v9, 7 bitop3:0x6c
	v_lshlrev_b32_e32 v6, 4, v6
	v_lshl_or_b32 v3, v3, 7, v6
	v_cmp_le_u32_e32 vcc, v7, v0
	v_add_u32_e32 v51, 0x14000, v3
	v_mov_b32_e32 v8, v1
	v_cndmask_b32_e64 v3, 0, 1, vcc
	v_cmp_ge_u32_e32 vcc, v7, v0
	v_mov_b32_e32 v7, v1
	v_add_u32_e32 v226, v51, v16
	v_cndmask_b32_e64 v6, 0, 1, vcc
	v_cndmask_b32_e64 v3, v6, v3, s[4:5]
	v_and_b32_e32 v3, 1, v3
	v_cmp_eq_u32_e64 s[42:43], 1, v3
	v_lshrrev_b32_e32 v3, 1, v0
	v_bitop3_b32 v3, v3, v9, 7 bitop3:0x6c
	v_lshlrev_b32_e32 v3, 4, v3
	v_lshl_or_b32 v0, v0, 7, v3
	v_add_u32_e32 v52, 0x14000, v0
	v_bitop3_b32 v0, v2, v20, 1 bitop3:0x6c
	v_lshlrev_b32_e32 v192, 4, v0
	v_bitop3_b32 v0, v19, v20, 2 bitop3:0x36
	v_lshlrev_b32_e32 v193, 4, v0
	v_bitop3_b32 v0, v19, v20, 4 bitop3:0x36
	v_lshlrev_b32_e32 v195, 4, v0
	v_bitop3_b32 v0, v19, v20, 6 bitop3:0x36
	v_lshlrev_b32_e32 v196, 4, v0
	v_lshlrev_b32_e32 v0, 13, v19
	v_lshl_add_u64 v[168:169], v[4:5], 0, v[0:1]
	v_mov_b32_e32 v0, v1
	v_mov_b32_e32 v2, v1
	v_mov_b32_e32 v3, v1
	v_mov_b32_e32 v4, v1
	v_mov_b32_e32 v5, v1
	v_mov_b32_e32 v6, v1
	v_mov_b32_e32 v9, v1
	v_add_u32_e32 v227, v52, v16
	v_mov_b64_e32 v[30:31], v[14:15]
	v_mov_b64_e32 v[46:47], v[14:15]
	v_mov_b64_e32 v[62:63], v[14:15]
	v_mov_b64_e32 v[78:79], v[14:15]
	s_movk_i32 s89, 0x82
	v_mov_b64_e32 v[28:29], v[12:13]
	v_mov_b64_e32 v[26:27], v[10:11]
	v_mov_b64_e32 v[24:25], v[8:9]
	v_mov_b64_e32 v[22:23], v[6:7]
	v_mov_b64_e32 v[20:21], v[4:5]
	v_mov_b64_e32 v[18:19], v[2:3]
	v_mov_b64_e32 v[16:17], v[0:1]
	v_mov_b64_e32 v[44:45], v[12:13]
	v_mov_b64_e32 v[42:43], v[10:11]
	v_mov_b64_e32 v[40:41], v[8:9]
	v_mov_b64_e32 v[38:39], v[6:7]
	v_mov_b64_e32 v[36:37], v[4:5]
	v_mov_b64_e32 v[34:35], v[2:3]
	v_mov_b64_e32 v[32:33], v[0:1]
	v_mov_b64_e32 v[60:61], v[12:13]
	v_mov_b64_e32 v[58:59], v[10:11]
	v_mov_b64_e32 v[56:57], v[8:9]
	v_mov_b64_e32 v[54:55], v[6:7]
	v_mov_b64_e32 v[52:53], v[4:5]
	v_mov_b64_e32 v[50:51], v[2:3]
	v_mov_b64_e32 v[48:49], v[0:1]
	v_mov_b64_e32 v[76:77], v[12:13]
	v_mov_b64_e32 v[74:75], v[10:11]
	v_mov_b64_e32 v[72:73], v[8:9]
	v_mov_b64_e32 v[70:71], v[6:7]
	v_mov_b64_e32 v[68:69], v[4:5]
	v_mov_b64_e32 v[66:67], v[2:3]
	v_mov_b64_e32 v[64:65], v[0:1]
	s_mov_b32 s81, s49
	v_mov_b64_e32 v[6:7], 0
	v_mov_b64_e32 v[8:9], 0
	v_mov_b64_e32 v[10:11], 0
	v_and_b32_e32 v113, 15, v148
	v_bfe_u32 v114, v148, 5, 1
	v_lshlrev_b32_e32 v115, 2, v113
	v_and_b32_e32 v115, 12, v115
	v_lshrrev_b32_e32 v116, 2, v113
	v_or_b32_e32 v115, v115, v116
	v_xor_b32_e32 v115, v115, v114
	v_xor_b32_e32 v116, 0, v115
	v_lshlrev_b32_e32 v184, 4, v116
	v_xor_b32_e32 v116, 2, v115
	v_lshlrev_b32_e32 v185, 4, v116
	v_xor_b32_e32 v116, 4, v115
	v_lshlrev_b32_e32 v186, 4, v116
	v_xor_b32_e32 v116, 6, v115
	v_lshlrev_b32_e32 v187, 4, v116
	v_xor_b32_e32 v116, 8, v115
	v_lshlrev_b32_e32 v188, 4, v116
	v_xor_b32_e32 v116, 10, v115
	v_lshlrev_b32_e32 v189, 4, v116
	v_xor_b32_e32 v116, 12, v115
	v_lshlrev_b32_e32 v190, 4, v116
	v_xor_b32_e32 v116, 14, v115
	v_lshlrev_b32_e32 v191, 4, v116
	v_lshlrev_b32_e32 v116, 2, v149
	v_and_b32_e32 v116, 12, v116
	v_bfe_u32 v117, v149, 2, 2
	v_or_b32_e32 v116, v116, v117
	v_xor_b32_e32 v116, v116, v113
	v_lshlrev_b32_e32 v116, 4, v116
	v_lshl_or_b32 v173, v149, 8, v116
	v_add_u32_e32 v174, 0x2000, v173
	v_and_b32_e32 v116, 3, v148
	v_bfe_u32 v117, v148, 2, 2
	v_bfe_u32 v118, v148, 4, 1
	v_and_b32_e32 v119, 1, v116
	v_lshl_or_b32 v119, v118, 1, v119
	v_lshlrev_b32_e32 v120, 1, v114
	v_xor_b32_e32 v119, v119, v120
	v_lshl_or_b32 v119, v117, 2, v119
	v_lshlrev_b32_e32 v119, 4, v119
	v_lshrrev_b32_e32 v120, 1, v116
	v_lshl_or_b32 v119, v120, 3, v119
	v_lshl_add_u32 v120, v114, 3, v117
	v_lshl_or_b32 v119, v120, 8, v119
	v_add_u32_e32 v197, 0x4000, v119
	v_xor_b32_e32 v198, 64, v197
	v_xor_b32_e32 v199, 0x80, v197
	v_xor_b32_e32 v200, 0xc0, v197
	v_xor_b32_e32 v201, 16, v197
	v_xor_b32_e32 v202, 16, v198
	v_xor_b32_e32 v203, 16, v199
	v_xor_b32_e32 v204, 16, v200
	s_branch .LBB0_1146

.LBB0_1146:
	s_and_b32 s32, s81, 1
	s_lshl_b32 s32, s32, 9
	s_cmp_gt_u32 s81, 3
	s_cselect_b64 s[82:83], -1, 0
	s_mov_b64 s[44:45], -1
	s_and_b64 vcc, exec, s[82:83]
	s_cbranch_vccnz .LBB0_1148
	s_add_i32 s48, s89, 0xffffff81
	s_and_b64 s[44:45], s[4:5], exec
	s_cselect_b32 s44, s81, s48
	s_lshl_b32 s44, s44, 6
	s_or_b32 s80, s44, s87
	s_mov_b64 s[44:45], 0

.LBB0_1150:
	s_waitcnt vmcnt(7)
	v_cvt_f32_f16_e32 v2, v156
	v_cvt_f32_f16_e32 v0, v142
	v_cvt_f32_f16_sdwa v3, v156 dst_sel:DWORD dst_unused:UNUSED_PAD src0_sel:WORD_1
	v_and_b32_e32 v5, 0xffff0000, v138
	v_exp_f32_e32 v114, v2
	v_exp_f32_e64 v116, -v2
	v_cvt_f32_f16_sdwa v2, v142 dst_sel:DWORD dst_unused:UNUSED_PAD src0_sel:WORD_1
	v_exp_f32_e32 v115, v3
	v_exp_f32_e64 v117, -v3
	v_lshlrev_b32_e32 v4, 16, v138
	v_lshlrev_b32_e32 v14, 16, v8
	v_and_b32_e32 v15, 0xffff0000, v8
	v_pk_mul_f32 v[114:115], v[114:115], v[14:15]
	v_pk_mul_f32 v[116:117], v[116:117], v[4:5]
	v_cvt_f32_f16_e32 v4, v157
	v_cvt_f32_f16_e32 v3, v143
	v_exp_f32_e32 v14, v4
	v_exp_f32_e64 v118, -v4
	v_cvt_f32_f16_sdwa v5, v157 dst_sel:DWORD dst_unused:UNUSED_PAD src0_sel:WORD_1
	v_cvt_f32_f16_sdwa v4, v143 dst_sel:DWORD dst_unused:UNUSED_PAD src0_sel:WORD_1
	v_lshlrev_b32_e32 v12, 16, v139
	v_exp_f32_e32 v15, v5
	v_exp_f32_e64 v119, -v5
	v_and_b32_e32 v13, 0xffff0000, v139
	v_lshlrev_b32_e32 v112, 16, v9
	v_and_b32_e32 v113, 0xffff0000, v9
	v_pk_mul_f32 v[120:121], v[14:15], v[112:113]
	v_pk_mul_f32 v[118:119], v[118:119], v[12:13]
	s_waitcnt vmcnt(6)
	v_cvt_f32_f16_e32 v12, v158
	v_cvt_f32_f16_e32 v5, v144
	v_cvt_f32_f16_sdwa v13, v158 dst_sel:DWORD dst_unused:UNUSED_PAD src0_sel:WORD_1
	v_lshlrev_b32_e32 v14, 16, v140
	v_exp_f32_e32 v126, v12
	v_exp_f32_e64 v228, -v12
	v_cvt_f32_f16_sdwa v12, v144 dst_sel:DWORD dst_unused:UNUSED_PAD src0_sel:WORD_1
	v_exp_f32_e32 v127, v13
	v_exp_f32_e64 v229, -v13
	v_and_b32_e32 v15, 0xffff0000, v140
	v_lshlrev_b32_e32 v122, 16, v10
	v_and_b32_e32 v123, 0xffff0000, v10
	v_pk_mul_f32 v[122:123], v[126:127], v[122:123]
	v_pk_mul_f32 v[126:127], v[228:229], v[14:15]
	v_cvt_f32_f16_e32 v14, v159
	v_cvt_f32_f16_e32 v13, v145
	v_cvt_f32_f16_sdwa v15, v159 dst_sel:DWORD dst_unused:UNUSED_PAD src0_sel:WORD_1
	v_exp_f32_e32 v228, v14
	v_exp_f32_e64 v230, -v14
	v_cvt_f32_f16_sdwa v14, v145 dst_sel:DWORD dst_unused:UNUSED_PAD src0_sel:WORD_1
	v_exp_f32_e32 v229, v15
	v_exp_f32_e64 v231, -v15
	v_lshlrev_b32_e32 v112, 16, v141
	v_and_b32_e32 v113, 0xffff0000, v141
	v_lshlrev_b32_e32 v124, 16, v11
	v_and_b32_e32 v125, 0xffff0000, v11
	v_pk_mul_f32 v[124:125], v[228:229], v[124:125]
	v_pk_mul_f32 v[228:229], v[230:231], v[112:113]
	v_cvt_pk_bf16_f32 v112, v114, v115
	v_cvt_pk_bf16_f32 v115, v124, v125
	s_waitcnt vmcnt(3)
	v_cvt_f32_f16_e32 v15, v164
	v_cvt_f32_f16_sdwa v124, v164 dst_sel:DWORD dst_unused:UNUSED_PAD src0_sel:WORD_1
	v_cvt_pk_bf16_f32 v114, v122, v123
	v_cvt_pk_bf16_f32 v113, v120, v121
	v_exp_f32_e32 v120, v15
	v_exp_f32_e32 v121, v124
	v_cvt_pk_bf16_f32 v116, v116, v117
	v_cvt_pk_bf16_f32 v117, v118, v119
	v_exp_f32_e64 v122, -v15
	v_cvt_pk_bf16_f32 v118, v126, v127
	v_cvt_pk_bf16_f32 v119, v228, v229
	ds_write_b128 v173, v[112:115]
	ds_write_b128 v173, v[116:119] offset:16384
	v_lshlrev_b32_e32 v116, 16, v6
	v_and_b32_e32 v117, 0xffff0000, v6
	v_pk_mul_f32 v[116:117], v[120:121], v[116:117]
	v_exp_f32_e64 v123, -v124
	v_lshlrev_b32_e32 v112, 16, v160
	v_and_b32_e32 v113, 0xffff0000, v160
	v_pk_mul_f32 v[120:121], v[122:123], v[112:113]
	v_cvt_f32_f16_e32 v123, v165
	v_cvt_f32_f16_sdwa v15, v165 dst_sel:DWORD dst_unused:UNUSED_PAD src0_sel:WORD_1
	v_exp_f32_e32 v112, v123
	v_exp_f32_e64 v122, -v123
	v_exp_f32_e32 v113, v15
	v_exp_f32_e64 v123, -v15
	v_lshlrev_b32_e32 v114, 16, v161
	v_and_b32_e32 v115, 0xffff0000, v161
	v_lshlrev_b32_e32 v118, 16, v7
	v_and_b32_e32 v119, 0xffff0000, v7
	v_pk_mul_f32 v[118:119], v[112:113], v[118:119]
	s_waitcnt vmcnt(2)
	v_cvt_f32_f16_e32 v15, v166
	v_cvt_f32_f16_sdwa v175, v166 dst_sel:DWORD dst_unused:UNUSED_PAD src0_sel:WORD_1
	v_lshlrev_b32_e32 v112, 16, v162
	v_exp_f32_e32 v228, v15
	v_exp_f32_e64 v230, -v15
	v_exp_f32_e32 v229, v175
	v_exp_f32_e64 v231, -v175
	v_and_b32_e32 v113, 0xffff0000, v162
	v_cvt_f32_f16_e32 v175, v167
	v_lshlrev_b32_e32 v124, 16, v170
	v_and_b32_e32 v125, 0xffff0000, v170
	v_pk_mul_f32 v[124:125], v[228:229], v[124:125]
	v_pk_mul_f32 v[228:229], v[230:231], v[112:113]
	v_cvt_f32_f16_sdwa v15, v167 dst_sel:DWORD dst_unused:UNUSED_PAD src0_sel:WORD_1
	v_exp_f32_e32 v112, v175
	v_exp_f32_e64 v230, -v175
	v_cvt_f32_f16_sdwa v194, v145 dst_sel:DWORD dst_unused:UNUSED_PAD src0_sel:WORD_1
	v_exp_f32_e32 v113, v15
	v_exp_f32_e64 v231, -v15
	v_pk_mul_f32 v[122:123], v[122:123], v[114:115]
	v_lshlrev_b32_e32 v114, 16, v163
	v_lshlrev_b32_e32 v126, 16, v171
	v_and_b32_e32 v127, 0xffff0000, v171
	v_and_b32_e32 v115, 0xffff0000, v163
	v_pk_mul_f32 v[126:127], v[112:113], v[126:127]
	v_pk_mul_f32 v[230:231], v[230:231], v[114:115]
	v_cvt_pk_bf16_f32 v112, v116, v117
	v_cvt_pk_bf16_f32 v113, v118, v119
	v_cvt_pk_bf16_f32 v114, v124, v125
	v_cvt_pk_bf16_f32 v115, v126, v127
	v_cvt_pk_bf16_f32 v116, v120, v121
	v_cvt_pk_bf16_f32 v117, v122, v123
	v_cvt_pk_bf16_f32 v118, v228, v229
	v_cvt_pk_bf16_f32 v119, v230, v231
	ds_write_b128 v174, v[112:115]
	ds_write_b128 v174, v[116:119] offset:16384
	s_waitcnt vmcnt(1)
	ds_write_b128 v211, v[128:131] offset:49152
	s_waitcnt vmcnt(0)
	ds_write_b128 v211, v[132:135] offset:57344
	s_and_saveexec_b64 s[44:45], s[6:7]
	s_cbranch_execz .LBB0_1152
	v_exp_f32_e32 v112, v0
	v_exp_f32_e32 v113, v2
	v_exp_f32_e32 v114, v3
	v_exp_f32_e32 v115, v4
	v_exp_f32_e32 v2, v5
	v_exp_f32_e32 v3, v12
	v_exp_f32_e32 v4, v13
	v_exp_f32_e32 v5, v14
	v_add_u32_e32 v12, s32, v176
	ds_write_b128 v12, v[112:115]
	ds_write_b128 v12, v[2:5] offset:32

.LBB0_1162:
	s_cmp_lg_u64 s[8:9], 0
	s_cbranch_scc0 .Lscan_nodecay
	s_cmp_eq_u32 s81, 0
	s_cbranch_scc1 .Lscan_nodecay
	s_xor_b32 s44, s32, 0x200
	v_add_u32_e32 v0, s44, v183
	ds_read_b128 v[2:5], v0 offset:0
	ds_read_b128 v[12:15], v0 offset:32
	ds_read_b128 v[112:115], v0 offset:64
	ds_read_b128 v[116:119], v0 offset:96
	ds_read_b128 v[120:123], v0 offset:128
	ds_read_b128 v[124:127], v0 offset:160
	s_waitcnt lgkmcnt(5)
	v_pk_mul_f32 v[64:65], v[64:65], v[2:3]
	v_pk_mul_f32 v[66:67], v[66:67], v[4:5]
	ds_read_b128 v[2:5], v0 offset:192
	s_waitcnt lgkmcnt(5)
	v_pk_mul_f32 v[68:69], v[68:69], v[12:13]
	v_pk_mul_f32 v[70:71], v[70:71], v[14:15]
	ds_read_b128 v[12:15], v0 offset:224
	s_waitcnt lgkmcnt(5)
	v_pk_mul_f32 v[72:73], v[72:73], v[112:113]
	v_pk_mul_f32 v[74:75], v[74:75], v[114:115]
	ds_read_b128 v[112:115], v0 offset:256
	s_waitcnt lgkmcnt(5)
	v_pk_mul_f32 v[76:77], v[76:77], v[116:117]
	v_pk_mul_f32 v[78:79], v[78:79], v[118:119]
	ds_read_b128 v[116:119], v0 offset:288
	s_waitcnt lgkmcnt(5)
	v_pk_mul_f32 v[48:49], v[48:49], v[120:121]
	v_pk_mul_f32 v[50:51], v[50:51], v[122:123]
	ds_read_b128 v[120:123], v0 offset:320
	s_waitcnt lgkmcnt(5)
	v_pk_mul_f32 v[52:53], v[52:53], v[124:125]
	v_pk_mul_f32 v[54:55], v[54:55], v[126:127]
	ds_read_b128 v[124:127], v0 offset:352
	s_waitcnt lgkmcnt(5)
	v_pk_mul_f32 v[56:57], v[56:57], v[2:3]
	v_pk_mul_f32 v[58:59], v[58:59], v[4:5]
	ds_read_b128 v[2:5], v0 offset:384
	s_waitcnt lgkmcnt(5)
	v_pk_mul_f32 v[60:61], v[60:61], v[12:13]
	v_pk_mul_f32 v[62:63], v[62:63], v[14:15]
	ds_read_b128 v[12:15], v0 offset:416
	s_waitcnt lgkmcnt(5)
	v_pk_mul_f32 v[32:33], v[32:33], v[112:113]
	v_pk_mul_f32 v[34:35], v[34:35], v[114:115]
	ds_read_b128 v[112:115], v0 offset:448
	s_waitcnt lgkmcnt(5)
	v_pk_mul_f32 v[36:37], v[36:37], v[116:117]
	v_pk_mul_f32 v[38:39], v[38:39], v[118:119]
	ds_read_b128 v[116:119], v0 offset:480
	s_waitcnt lgkmcnt(5)
	v_pk_mul_f32 v[40:41], v[40:41], v[120:121]
	v_pk_mul_f32 v[42:43], v[42:43], v[122:123]
	s_waitcnt lgkmcnt(4)
	v_pk_mul_f32 v[44:45], v[44:45], v[124:125]
	v_pk_mul_f32 v[46:47], v[46:47], v[126:127]
	s_waitcnt lgkmcnt(3)
	v_pk_mul_f32 v[16:17], v[16:17], v[2:3]
	v_pk_mul_f32 v[18:19], v[18:19], v[4:5]
	s_waitcnt lgkmcnt(2)
	v_pk_mul_f32 v[20:21], v[20:21], v[12:13]
	v_pk_mul_f32 v[22:23], v[22:23], v[14:15]
	s_waitcnt lgkmcnt(1)
	v_pk_mul_f32 v[24:25], v[24:25], v[112:113]
	v_pk_mul_f32 v[26:27], v[26:27], v[114:115]
	s_waitcnt lgkmcnt(0)
	v_pk_mul_f32 v[28:29], v[28:29], v[116:117]
	v_pk_mul_f32 v[30:31], v[30:31], v[118:119]

.Lscan_loads_ret:
.Lscan_tail_w03:
	s_and_saveexec_b64 s[44:45], s[8:9]
	s_cbranch_execz .LBB0_1145
	v_add_u32_e32 v0, v180, v192
	ds_read_b128 v[120:123], v0 offset:49152
	ds_read_b64_tr_b16 v[124:125], v197 offset:0
	ds_read_b64_tr_b16 v[126:127], v201 offset:1024
	ds_read_b64_tr_b16 v[12:13], v198 offset:0
	ds_read_b64_tr_b16 v[14:15], v202 offset:1024
	ds_read_b64_tr_b16 v[112:113], v199 offset:0
	ds_read_b64_tr_b16 v[114:115], v203 offset:1024
	ds_read_b64_tr_b16 v[116:117], v200 offset:0
	ds_read_b64_tr_b16 v[118:119], v204 offset:1024
	v_add_u32_e32 v0, v180, v193
	ds_read_b128 v[2:5], v0 offset:49152
	s_waitcnt lgkmcnt(7)
	v_mfma_f32_32x32x16_bf16 v[64:79], v[124:127], v[120:123], v[64:79]
	ds_read_b64_tr_b16 v[124:125], v197 offset:4096
	ds_read_b64_tr_b16 v[126:127], v201 offset:5120
	s_waitcnt lgkmcnt(7)
	v_mfma_f32_32x32x16_bf16 v[48:63], v[12:15], v[120:123], v[48:63]
	ds_read_b64_tr_b16 v[12:13], v198 offset:4096
	ds_read_b64_tr_b16 v[14:15], v202 offset:5120
	s_waitcnt lgkmcnt(7)
	v_mfma_f32_32x32x16_bf16 v[32:47], v[112:115], v[120:123], v[32:47]
	ds_read_b64_tr_b16 v[112:113], v199 offset:4096
	ds_read_b64_tr_b16 v[114:115], v203 offset:5120
	s_waitcnt lgkmcnt(7)
	v_mfma_f32_32x32x16_bf16 v[16:31], v[116:119], v[120:123], v[16:31]
	ds_read_b64_tr_b16 v[116:117], v200 offset:4096
	ds_read_b64_tr_b16 v[118:119], v204 offset:5120
	v_add_u32_e32 v0, v180, v195
	ds_read_b128 v[120:123], v0 offset:49152
	s_waitcnt lgkmcnt(7)
	v_mfma_f32_32x32x16_bf16 v[64:79], v[124:127], v[2:5], v[64:79]
	ds_read_b64_tr_b16 v[124:125], v197 offset:8192
	ds_read_b64_tr_b16 v[126:127], v201 offset:9216
	s_waitcnt lgkmcnt(7)
	v_mfma_f32_32x32x16_bf16 v[48:63], v[12:15], v[2:5], v[48:63]
	ds_read_b64_tr_b16 v[12:13], v198 offset:8192
	ds_read_b64_tr_b16 v[14:15], v202 offset:9216
	s_waitcnt lgkmcnt(7)
	v_mfma_f32_32x32x16_bf16 v[32:47], v[112:115], v[2:5], v[32:47]
	ds_read_b64_tr_b16 v[112:113], v199 offset:8192
	ds_read_b64_tr_b16 v[114:115], v203 offset:9216
	s_waitcnt lgkmcnt(7)
	v_mfma_f32_32x32x16_bf16 v[16:31], v[116:119], v[2:5], v[16:31]
	ds_read_b64_tr_b16 v[116:117], v200 offset:8192
	ds_read_b64_tr_b16 v[118:119], v204 offset:9216
	v_add_u32_e32 v0, v180, v196
	ds_read_b128 v[2:5], v0 offset:49152
	s_waitcnt lgkmcnt(7)
	v_mfma_f32_32x32x16_bf16 v[64:79], v[124:127], v[120:123], v[64:79]
	ds_read_b64_tr_b16 v[124:125], v197 offset:12288
	ds_read_b64_tr_b16 v[126:127], v201 offset:13312
	s_waitcnt lgkmcnt(7)
	v_mfma_f32_32x32x16_bf16 v[48:63], v[12:15], v[120:123], v[48:63]
	ds_read_b64_tr_b16 v[12:13], v198 offset:12288
	ds_read_b64_tr_b16 v[14:15], v202 offset:13312
	s_waitcnt lgkmcnt(7)
	v_mfma_f32_32x32x16_bf16 v[32:47], v[112:115], v[120:123], v[32:47]
	ds_read_b64_tr_b16 v[112:113], v199 offset:12288
	ds_read_b64_tr_b16 v[114:115], v203 offset:13312
	s_waitcnt lgkmcnt(7)
	v_mfma_f32_32x32x16_bf16 v[16:31], v[116:119], v[120:123], v[16:31]
	ds_read_b64_tr_b16 v[116:117], v200 offset:12288
	ds_read_b64_tr_b16 v[118:119], v204 offset:13312
	s_waitcnt lgkmcnt(6)
	v_mfma_f32_32x32x16_bf16 v[64:79], v[124:127], v[2:5], v[64:79]
	s_waitcnt lgkmcnt(4)
	v_mfma_f32_32x32x16_bf16 v[48:63], v[12:15], v[2:5], v[48:63]
	s_waitcnt lgkmcnt(2)
	v_mfma_f32_32x32x16_bf16 v[32:47], v[112:115], v[2:5], v[32:47]
	s_waitcnt lgkmcnt(0)
	v_mfma_f32_32x32x16_bf16 v[16:31], v[116:119], v[2:5], v[16:31]
	s_branch .LBB0_1145

.LBB0_1262:
	v_lshl_add_u64 v[4:5], s[20:21], 0, v[150:151]
	v_lshl_add_u64 v[6:7], s[16:17], 0, v[150:151]
	global_load_dword v3, v[4:5], off
	v_add_co_u32_e32 v4, vcc, 0x2684000, v6
	s_nop 1
	v_addc_co_u32_e32 v5, vcc, 0, v7, vcc
	v_add_co_u32_e32 v8, vcc, 0x26ba000, v6
	s_nop 1
	v_addc_co_u32_e32 v9, vcc, 0, v7, vcc
	v_add_co_u32_e32 v10, vcc, 0x26f0000, v6
	global_load_dword v12, v[4:5], off
	global_load_dword v13, v[8:9], off
	v_addc_co_u32_e32 v11, vcc, 0, v7, vcc
	v_add_co_u32_e32 v4, vcc, 0x2726000, v6
	s_waitcnt vmcnt(1)
	v_add_f32_e32 v3, v3, v12
	v_addc_co_u32_e32 v5, vcc, 0, v7, vcc
	v_add_co_u32_e32 v8, vcc, 0x275c000, v6
	global_load_dword v14, v[10:11], off
	global_load_dword v15, v[4:5], off
	v_addc_co_u32_e32 v9, vcc, 0, v7, vcc
	v_add_co_u32_e32 v4, vcc, 0x2792000, v6
	s_waitcnt vmcnt(2)
	v_add_f32_e32 v3, v3, v13
	v_addc_co_u32_e32 v5, vcc, 0, v7, vcc
	v_add_co_u32_e32 v10, vcc, 0x27c8000, v6
	global_load_dword v16, v[8:9], off
	global_load_dword v17, v[4:5], off
	v_addc_co_u32_e32 v11, vcc, 0, v7, vcc
	v_add_co_u32_e32 v4, vcc, 0x27fe000, v6
	s_waitcnt vmcnt(3)
	v_add_f32_e32 v3, v3, v14
	v_addc_co_u32_e32 v5, vcc, 0, v7, vcc
	v_add_co_u32_e32 v8, vcc, 0x2834000, v6
	global_load_dword v18, v[10:11], off
	global_load_dword v19, v[4:5], off
	v_addc_co_u32_e32 v9, vcc, 0, v7, vcc
	v_add_co_u32_e32 v4, vcc, 0x286a000, v6
	s_waitcnt vmcnt(4)
	v_add_f32_e32 v3, v3, v15
	v_addc_co_u32_e32 v5, vcc, 0, v7, vcc
	v_add_co_u32_e32 v10, vcc, 0x28a0000, v6
	global_load_dword v20, v[8:9], off
	global_load_dword v21, v[4:5], off
	v_addc_co_u32_e32 v11, vcc, 0, v7, vcc
	v_add_co_u32_e32 v4, vcc, 0x28d6000, v6
	s_waitcnt vmcnt(5)
	v_add_f32_e32 v3, v3, v16
	v_addc_co_u32_e32 v5, vcc, 0, v7, vcc
	v_add_co_u32_e32 v8, vcc, 0x290c000, v6
	global_load_dword v22, v[10:11], off
	global_load_dword v23, v[4:5], off
	v_addc_co_u32_e32 v9, vcc, 0, v7, vcc
	v_add_co_u32_e32 v4, vcc, 0x2942000, v6
	s_waitcnt vmcnt(6)
	v_add_f32_e32 v3, v3, v17
	v_addc_co_u32_e32 v5, vcc, 0, v7, vcc
	v_add_co_u32_e32 v10, vcc, 0x2978000, v6
	global_load_dword v8, v[8:9], off
	s_nop 0
	global_load_dword v9, v[4:5], off
	v_addc_co_u32_e32 v11, vcc, 0, v7, vcc
	v_add_co_u32_e32 v4, vcc, 0x29ae000, v6
	s_waitcnt vmcnt(7)
	v_add_f32_e32 v3, v3, v18
	v_addc_co_u32_e32 v5, vcc, 0, v7, vcc
	global_load_dword v6, v[10:11], off
	s_nop 0
	global_load_dword v4, v[4:5], off
	s_waitcnt vmcnt(8)
	v_add_f32_e32 v3, v3, v19
	v_add_co_u32_e32 v1, vcc, s24, v1
	s_xor_b64 s[22:23], vcc, -1
	s_add_u32 s20, s20, 0x800
	s_addc_u32 s21, s21, 0
	s_waitcnt vmcnt(7)
	v_add_f32_e32 v3, v3, v20
	s_waitcnt vmcnt(6)
	v_add_f32_e32 v3, v3, v21
	s_add_u32 s16, s16, 0x800
	s_addc_u32 s17, s17, 0
	s_and_b64 s[22:23], exec, s[22:23]
	s_or_b64 s[18:19], s[22:23], s[18:19]
	s_waitcnt vmcnt(5)
	v_add_f32_e32 v3, v3, v22
	s_waitcnt vmcnt(4)
	v_add_f32_e32 v3, v3, v23
	s_waitcnt vmcnt(3)
	v_add_f32_e32 v3, v3, v8
	s_waitcnt vmcnt(2)
	v_add_f32_e32 v3, v3, v9
	s_waitcnt vmcnt(1)
	v_add_f32_e32 v3, v3, v6
	s_waitcnt vmcnt(0)
	v_add_f32_e32 v3, v3, v4
	ds_write_b32 v2, v3
	v_add_u32_e32 v2, 0x800, v2
	s_andn2_b64 exec, exec, s[18:19]
	s_cbranch_execnz .LBB0_1262
	s_or_b64 exec, exec, s[18:19]
	v_ashrrev_i32_e32 v1, 1, v0
	v_lshlrev_b32_e32 v0, 2, v0
	v_and_b32_e32 v0, 0xfc, v0
	v_cmp_lt_i32_e32 vcc, v125, v124
	v_lshlrev_b32_e32 v64, 1, v0
	v_lshlrev_b32_e32 v36, 2, v0
	v_cndmask_b32_e32 v0, v123, v125, vcc
	v_cmp_lt_i32_e32 vcc, v126, v124
	v_lshlrev_b32_e32 v131, 2, v0
	s_waitcnt lgkmcnt(0)
	v_cndmask_b32_e32 v0, v123, v126, vcc
	v_cmp_lt_i32_e32 vcc, v127, v124
	v_lshlrev_b32_e32 v132, 2, v0
	s_barrier
	v_cndmask_b32_e32 v0, v123, v127, vcc
	v_cmp_lt_i32_e32 vcc, v128, v124
	v_lshlrev_b32_e32 v133, 2, v0
	s_nop 0
	v_cndmask_b32_e32 v0, v123, v128, vcc
	v_cmp_lt_i32_e32 vcc, v129, v124
	v_lshlrev_b32_e32 v134, 2, v0
	v_and_b32_e32 v38, 0xffffffe0, v1
	v_cndmask_b32_e32 v0, v123, v129, vcc
	v_cmp_lt_i32_e32 vcc, v130, v124
	v_lshlrev_b32_e32 v135, 2, v0
	v_mov_b32_e32 v37, v65
	v_cndmask_b32_e32 v0, v123, v130, vcc
	v_lshlrev_b32_e32 v136, 2, v0
	ds_read_b128 v[0:3], v36
	ds_read_b128 v[4:7], v36 offset:1024
	ds_read_b128 v[16:19], v36 offset:8192
	ds_read_b128 v[8:11], v36 offset:2048
	ds_read_b128 v[12:15], v36 offset:3072
	ds_read_b128 v[24:27], v36 offset:9216
	v_lshl_add_u64 v[68:69], s[66:67], 0, v[64:65]
	s_waitcnt lgkmcnt(3)
	v_pk_add_f32 v[76:77], v[16:17], 1.0 op_sel_hi:[1,0]
	v_pk_add_f32 v[78:79], v[18:19], 1.0 op_sel_hi:[1,0]
	ds_read_b128 v[28:31], v36 offset:10240
	ds_read_b128 v[16:19], v36 offset:4096
	ds_read_b128 v[20:23], v36 offset:5120
	ds_read_b128 v[32:35], v36 offset:11264
	s_waitcnt lgkmcnt(4)
	v_pk_add_f32 v[80:81], v[24:25], 1.0 op_sel_hi:[1,0]
	v_pk_add_f32 v[82:83], v[26:27], 1.0 op_sel_hi:[1,0]
	s_waitcnt lgkmcnt(3)
	v_pk_add_f32 v[84:85], v[28:29], 1.0 op_sel_hi:[1,0]
	v_pk_add_f32 v[86:87], v[30:31], 1.0 op_sel_hi:[1,0]
	ds_read_b128 v[24:27], v36 offset:6144
	ds_read_b128 v[28:31], v36 offset:7168
	v_lshl_add_u64 v[70:71], s[64:65], 0, v[36:37]
	s_mov_b32 s16, 0
	v_lshl_add_u64 v[72:73], s[82:83], 0, v[36:37]
	v_lshl_add_u64 v[74:75], s[84:85], 0, v[36:37]
	s_waitcnt lgkmcnt(2)
	v_pk_add_f32 v[88:89], v[32:33], 1.0 op_sel_hi:[1,0]
	v_pk_add_f32 v[90:91], v[34:35], 1.0 op_sel_hi:[1,0]
	v_lshl_add_u64 v[92:93], s[52:53], 0, v[36:37]
	v_lshl_add_u64 v[94:95], s[58:59], 0, v[64:65]
	v_add_u32_e32 v64, s3, v38
	global_load_dwordx4 v[200:203], v[72:73], off
	global_load_dwordx4 v[204:207], v[72:73], off offset:1024
	global_load_dwordx4 v[208:211], v[72:73], off offset:2048
	global_load_dwordx4 v[212:215], v[72:73], off offset:3072
	global_load_dwordx4 v[216:219], v[74:75], off
	global_load_dwordx4 v[220:223], v[74:75], off offset:1024
	global_load_dwordx4 v[224:227], v[74:75], off offset:2048
	global_load_dwordx4 v[228:231], v[74:75], off offset:3072
	s_waitcnt vmcnt(0)
.LBB0_1264:
	v_add_u32_e32 v32, s16, v64
	v_add_u32_e32 v34, 16, v32
	v_ashrrev_i32_e32 v33, 31, v32
	v_ashrrev_i32_e32 v35, 31, v34
	v_lshlrev_b64 v[98:99], 11, v[32:33]
	v_lshlrev_b64 v[32:33], 12, v[32:33]
	v_lshlrev_b64 v[96:97], 11, v[34:35]
	v_lshlrev_b64 v[108:109], 12, v[34:35]
	v_lshl_add_u64 v[36:37], v[68:69], 0, v[98:99]
	v_lshl_add_u64 v[38:39], v[70:71], 0, v[32:33]
	v_lshl_add_u64 v[110:111], v[92:93], 0, v[32:33]
	v_lshl_add_u64 v[32:33], v[68:69], 0, v[96:97]
	v_lshl_add_u64 v[34:35], v[70:71], 0, v[108:109]
	v_mov_b32_e32 v56, v200
	v_mov_b32_e32 v57, v201
	v_mov_b32_e32 v58, v202
	v_mov_b32_e32 v59, v203
	global_load_dwordx2 v[100:101], v[36:37], off
	global_load_dwordx2 v[102:103], v[36:37], off offset:512
	global_load_dwordx2 v[104:105], v[36:37], off offset:1024
	global_load_dwordx4 v[138:141], v[38:39], off
	global_load_dwordx4 v[52:55], v[38:39], off offset:1024
	global_load_dwordx2 v[106:107], v[36:37], off offset:1536
	global_load_dwordx4 v[60:63], v[38:39], off offset:2048
	global_load_dwordx4 v[48:51], v[38:39], off offset:3072
	global_load_dwordx2 v[112:113], v[32:33], off
	global_load_dwordx2 v[114:115], v[32:33], off offset:512
	global_load_dwordx2 v[142:143], v[32:33], off offset:1024
	global_load_dwordx2 v[144:145], v[32:33], off offset:1536
	global_load_dwordx4 v[44:47], v[34:35], off
	global_load_dwordx4 v[40:43], v[34:35], off offset:1024
	global_load_dwordx4 v[36:39], v[34:35], off offset:2048
	s_nop 0
	global_load_dwordx4 v[32:35], v[34:35], off offset:3072
	s_add_i32 s16, s16, 1
	s_cmp_lg_u32 s16, 16
	s_waitcnt vmcnt(15)
	v_and_b32_e32 v147, 0xffff0000, v100
	s_waitcnt vmcnt(7)
	v_and_b32_e32 v117, 0xffff0000, v112
	v_lshlrev_b32_e32 v146, 16, v100
	v_lshlrev_b32_e32 v116, 16, v112
	v_mov_b32_e32 v169, v147
	v_mov_b32_e32 v168, v117
	v_lshlrev_b32_e32 v152, 16, v101
	v_lshlrev_b32_e32 v118, 16, v113
	v_mov_b32_e32 v167, v146
	v_mov_b32_e32 v166, v116
	v_pk_mul_f32 v[168:169], v[168:169], v[168:169]
	v_and_b32_e32 v153, 0xffff0000, v101
	v_and_b32_e32 v119, 0xffff0000, v113
	v_mov_b32_e32 v165, v152
	v_mov_b32_e32 v164, v118
	v_pk_fma_f32 v[166:167], v[166:167], v[166:167], v[168:169]
	v_lshlrev_b32_e32 v154, 16, v102
	s_waitcnt vmcnt(6)
	v_lshlrev_b32_e32 v112, 16, v114
	v_mov_b32_e32 v171, v153
	v_mov_b32_e32 v170, v119
	v_pk_fma_f32 v[164:165], v[164:165], v[164:165], v[166:167]
	v_and_b32_e32 v155, 0xffff0000, v102
	v_and_b32_e32 v113, 0xffff0000, v114
	v_mov_b32_e32 v177, v154
	v_mov_b32_e32 v176, v112
	v_pk_fma_f32 v[164:165], v[170:171], v[170:171], v[164:165]
	v_lshlrev_b32_e32 v156, 16, v103
	v_lshlrev_b32_e32 v114, 16, v115
	v_mov_b32_e32 v179, v155
	v_mov_b32_e32 v178, v113
	v_pk_fma_f32 v[164:165], v[176:177], v[176:177], v[164:165]
	v_and_b32_e32 v157, 0xffff0000, v103
	v_and_b32_e32 v115, 0xffff0000, v115
	v_mov_b32_e32 v173, v156
	v_mov_b32_e32 v172, v114
	v_pk_fma_f32 v[164:165], v[178:179], v[178:179], v[164:165]
	v_lshlrev_b32_e32 v158, 16, v104
	v_and_b32_e32 v159, 0xffff0000, v104
	s_waitcnt vmcnt(5)
	v_lshlrev_b32_e32 v104, 16, v142
	v_mov_b32_e32 v175, v157
	v_mov_b32_e32 v174, v115
	v_pk_fma_f32 v[164:165], v[172:173], v[172:173], v[164:165]
	v_lshlrev_b32_e32 v160, 16, v105
	v_and_b32_e32 v161, 0xffff0000, v105
	v_and_b32_e32 v105, 0xffff0000, v142
	v_mov_b32_e32 v185, v158
	v_mov_b32_e32 v184, v104
	v_pk_fma_f32 v[164:165], v[174:175], v[174:175], v[164:165]
	v_lshlrev_b32_e32 v162, 16, v106
	v_and_b32_e32 v163, 0xffff0000, v106
	v_lshlrev_b32_e32 v106, 16, v143
	v_mov_b32_e32 v187, v159
	v_mov_b32_e32 v186, v105
	v_pk_fma_f32 v[164:165], v[184:185], v[184:185], v[164:165]
	v_lshlrev_b32_e32 v120, 16, v107
	v_and_b32_e32 v121, 0xffff0000, v107
	v_and_b32_e32 v107, 0xffff0000, v143
	s_waitcnt vmcnt(4)
	v_lshlrev_b32_e32 v100, 16, v144
	v_and_b32_e32 v101, 0xffff0000, v144
	v_mov_b32_e32 v181, v160
	v_mov_b32_e32 v180, v106
	v_pk_fma_f32 v[164:165], v[186:187], v[186:187], v[164:165]
	v_lshlrev_b32_e32 v102, 16, v145
	v_and_b32_e32 v103, 0xffff0000, v145
	v_pk_mul_f32 v[144:145], v[162:163], v[162:163]
	v_mov_b32_e32 v183, v161
	v_pk_mul_f32 v[190:191], v[100:101], v[100:101]
	v_mov_b32_e32 v182, v107
	v_pk_fma_f32 v[164:165], v[180:181], v[180:181], v[164:165]
	v_mov_b32_e32 v193, v144
	v_mov_b32_e32 v192, v190
	v_pk_fma_f32 v[164:165], v[182:183], v[182:183], v[164:165]
	v_pk_mul_f32 v[142:143], v[120:121], v[120:121]
	v_pk_mul_f32 v[188:189], v[102:103], v[102:103]
	v_mov_b32_e32 v144, v191
	v_pk_add_f32 v[164:165], v[192:193], v[164:165]
	v_mov_b32_e32 v195, v142
	v_mov_b32_e32 v194, v188
	v_pk_add_f32 v[144:145], v[144:145], v[164:165]
	v_mov_b32_e32 v142, v189
	v_pk_add_f32 v[144:145], v[194:195], v[144:145]
	s_nop 0
	v_pk_add_f32 v[142:143], v[142:143], v[144:145]
	ds_bpermute_b32 v145, v131, v143
	ds_bpermute_b32 v144, v131, v142
	s_waitcnt lgkmcnt(0)
	v_pk_add_f32 v[142:143], v[142:143], v[144:145]
	ds_bpermute_b32 v145, v132, v143
	ds_bpermute_b32 v144, v132, v142
	s_waitcnt lgkmcnt(0)
	v_pk_add_f32 v[142:143], v[142:143], v[144:145]
	ds_bpermute_b32 v145, v133, v143
	ds_bpermute_b32 v144, v133, v142
	s_waitcnt lgkmcnt(0)
	v_pk_add_f32 v[142:143], v[142:143], v[144:145]
	ds_bpermute_b32 v145, v134, v143
	ds_bpermute_b32 v144, v134, v142
	s_waitcnt lgkmcnt(0)
	v_pk_add_f32 v[142:143], v[142:143], v[144:145]
	ds_bpermute_b32 v145, v135, v143
	ds_bpermute_b32 v144, v135, v142
	s_waitcnt lgkmcnt(0)
	v_pk_add_f32 v[142:143], v[142:143], v[144:145]
	ds_bpermute_b32 v145, v136, v143
	ds_bpermute_b32 v144, v136, v142
	s_waitcnt lgkmcnt(0)
	v_pk_add_f32 v[142:143], v[142:143], v[144:145]
	s_nop 0
	v_pk_fma_f32 v[142:143], v[142:143], s[14:15], v[66:67] op_sel_hi:[1,0,0]
	s_nop 0
	v_mul_f32_e32 v137, 0x4b800000, v143
	v_cmp_gt_f32_e32 vcc, s25, v143
	s_nop 1
	v_cndmask_b32_e32 v137, v143, v137, vcc
	v_rsq_f32_e32 v137, v137
	s_nop 0
	v_mul_f32_e32 v143, 0x45800000, v137
	v_cndmask_b32_e32 v144, v137, v143, vcc
	v_pk_mul_f32 v[146:147], v[144:145], v[146:147] op_sel_hi:[0,1]
	v_pk_mul_f32 v[152:153], v[144:145], v[152:153] op_sel_hi:[0,1]
	v_pk_mul_f32 v[56:57], v[56:57], v[146:147]
	v_pk_mul_f32 v[58:59], v[58:59], v[152:153]
	v_pk_fma_f32 v[56:57], v[0:1], v[56:57], v[138:139]
	v_pk_fma_f32 v[58:59], v[2:3], v[58:59], v[140:141]
	global_store_dwordx4 v[110:111], v[56:59], off
	v_mov_b32_e32 v138, v204
	v_mov_b32_e32 v139, v205
	v_mov_b32_e32 v140, v206
	v_mov_b32_e32 v141, v207
	v_pk_mul_f32 v[146:147], v[144:145], v[154:155] op_sel_hi:[0,1]
	v_pk_mul_f32 v[152:153], v[144:145], v[156:157] op_sel_hi:[0,1]
	v_pk_mul_f32 v[120:121], v[144:145], v[120:121] op_sel_hi:[0,1]
	v_cmp_gt_f32_e32 vcc, s25, v142
	s_waitcnt vmcnt(0)
	v_pk_mul_f32 v[138:139], v[138:139], v[146:147]
	v_pk_mul_f32 v[140:141], v[140:141], v[152:153]
	v_pk_fma_f32 v[52:53], v[4:5], v[138:139], v[52:53]
	v_pk_fma_f32 v[54:55], v[6:7], v[140:141], v[54:55]
	global_store_dwordx4 v[110:111], v[52:55], off offset:1024
	v_mov_b32_e32 v138, v208
	v_mov_b32_e32 v139, v209
	v_mov_b32_e32 v140, v210
	v_mov_b32_e32 v141, v211
	v_pk_mul_f32 v[146:147], v[144:145], v[158:159] op_sel_hi:[0,1]
	v_pk_mul_f32 v[152:153], v[144:145], v[160:161] op_sel_hi:[0,1]
	v_pk_mul_f32 v[138:139], v[146:147], v[138:139]
	v_pk_mul_f32 v[140:141], v[152:153], v[140:141]
	v_pk_fma_f32 v[60:61], v[8:9], v[138:139], v[60:61]
	v_pk_fma_f32 v[62:63], v[10:11], v[140:141], v[62:63]
	global_store_dwordx4 v[110:111], v[60:63], off offset:2048
	v_mov_b32_e32 v138, v212
	v_mov_b32_e32 v139, v213
	v_mov_b32_e32 v140, v214
	v_mov_b32_e32 v141, v215
	v_pk_mul_f32 v[146:147], v[144:145], v[162:163] op_sel_hi:[0,1]
	v_mov_b32_e32 v145, v61
	v_mov_b32_e32 v153, v63
	v_pk_mul_f32 v[138:139], v[146:147], v[138:139]
	v_pk_mul_f32 v[120:121], v[120:121], v[140:141]
	v_pk_fma_f32 v[48:49], v[12:13], v[138:139], v[48:49]
	v_pk_fma_f32 v[50:51], v[14:15], v[120:121], v[50:51]
	global_store_dwordx4 v[110:111], v[48:51], off offset:3072
	v_mov_b32_e32 v138, v200
	v_mov_b32_e32 v139, v201
	v_mov_b32_e32 v140, v202
	v_mov_b32_e32 v141, v203
	v_lshl_add_u64 v[120:121], v[92:93], 0, v[108:109]
	v_mul_f32_e32 v108, 0x4b800000, v142
	v_cndmask_b32_e32 v108, v142, v108, vcc
	v_rsq_f32_e32 v108, v108
	v_mov_b32_e32 v147, v62
	v_pk_mul_f32 v[154:155], v[48:49], v[48:49]
	v_pk_mul_f32 v[156:157], v[50:51], v[50:51]
	v_mul_f32_e32 v109, 0x45800000, v108
	v_cndmask_b32_e32 v142, v108, v109, vcc
	v_pk_mul_f32 v[108:109], v[142:143], v[116:117] op_sel_hi:[0,1]
	v_pk_mul_f32 v[110:111], v[142:143], v[118:119] op_sel_hi:[0,1]
	v_pk_mul_f32 v[112:113], v[142:143], v[112:113] op_sel_hi:[0,1]
	v_pk_mul_f32 v[114:115], v[142:143], v[114:115] op_sel_hi:[0,1]
	v_pk_mul_f32 v[104:105], v[142:143], v[104:105] op_sel_hi:[0,1]
	v_pk_mul_f32 v[106:107], v[142:143], v[106:107] op_sel_hi:[0,1]
	v_mov_b32_e32 v117, v52
	v_mov_b32_e32 v119, v53
	v_mov_b32_e32 v159, v154
	v_mov_b32_e32 v161, v156
	v_pk_mul_f32 v[108:109], v[138:139], v[108:109]
	v_pk_mul_f32 v[110:111], v[140:141], v[110:111]
	v_pk_fma_f32 v[44:45], v[0:1], v[108:109], v[44:45]
	v_pk_fma_f32 v[46:47], v[2:3], v[110:111], v[46:47]
	global_store_dwordx4 v[120:121], v[44:47], off
	v_mov_b32_e32 v108, v204
	v_mov_b32_e32 v109, v205
	v_mov_b32_e32 v110, v206
	v_mov_b32_e32 v111, v207
	v_mov_b32_e32 v139, v54
	v_mov_b32_e32 v141, v55
	v_pk_mul_f32 v[108:109], v[112:113], v[108:109]
	v_pk_mul_f32 v[110:111], v[114:115], v[110:111]
	v_pk_fma_f32 v[40:41], v[4:5], v[108:109], v[40:41]
	v_pk_fma_f32 v[42:43], v[6:7], v[110:111], v[42:43]
	global_store_dwordx4 v[120:121], v[40:43], off offset:1024
	v_mov_b32_e32 v108, v208
	v_mov_b32_e32 v109, v209
	v_mov_b32_e32 v110, v210
	v_mov_b32_e32 v111, v211
	v_mov_b32_e32 v113, v58
	v_mov_b32_e32 v112, v46
	v_mov_b32_e32 v115, v59
	v_mov_b32_e32 v114, v47
	v_mov_b32_e32 v116, v40
	v_mov_b32_e32 v118, v41
	v_mov_b32_e32 v138, v42
	v_mov_b32_e32 v140, v43
	v_pk_mul_f32 v[104:105], v[104:105], v[108:109]
	v_pk_mul_f32 v[106:107], v[106:107], v[110:111]
	v_pk_fma_f32 v[36:37], v[8:9], v[104:105], v[36:37]
	v_pk_fma_f32 v[38:39], v[10:11], v[106:107], v[38:39]
	global_store_dwordx4 v[120:121], v[36:39], off offset:2048
	v_mov_b32_e32 v104, v212
	v_mov_b32_e32 v105, v213
	v_mov_b32_e32 v106, v214
	v_mov_b32_e32 v107, v215
	v_lshl_add_u64 v[108:109], v[94:95], 0, v[98:99]
	v_pk_mul_f32 v[98:99], v[142:143], v[100:101] op_sel_hi:[0,1]
	v_pk_mul_f32 v[100:101], v[142:143], v[102:103] op_sel_hi:[0,1]
	v_mov_b32_e32 v111, v57
	v_mov_b32_e32 v110, v45
	v_mov_b32_e32 v103, v56
	v_mov_b32_e32 v102, v44
	v_pk_mul_f32 v[110:111], v[110:111], v[110:111]
	v_mov_b32_e32 v143, v60
	v_pk_fma_f32 v[102:103], v[102:103], v[102:103], v[110:111]
	v_mov_b32_e32 v142, v36
	v_pk_fma_f32 v[102:103], v[112:113], v[112:113], v[102:103]
	v_mov_b32_e32 v144, v37
	v_pk_fma_f32 v[102:103], v[114:115], v[114:115], v[102:103]
	v_mov_b32_e32 v146, v38
	v_pk_fma_f32 v[102:103], v[116:117], v[116:117], v[102:103]
	v_mov_b32_e32 v152, v39
	v_pk_fma_f32 v[102:103], v[118:119], v[118:119], v[102:103]
	v_pk_mul_f32 v[98:99], v[98:99], v[104:105]
	v_pk_mul_f32 v[100:101], v[100:101], v[106:107]
	v_pk_fma_f32 v[32:33], v[12:13], v[98:99], v[32:33]
	v_pk_fma_f32 v[34:35], v[14:15], v[100:101], v[34:35]
	global_store_dwordx4 v[120:121], v[32:35], off offset:3072
	v_mov_b32_e32 v98, v216
	v_mov_b32_e32 v99, v217
	v_mov_b32_e32 v100, v218
	v_mov_b32_e32 v101, v219
	v_pk_fma_f32 v[102:103], v[138:139], v[138:139], v[102:103]
	v_pk_mul_f32 v[104:105], v[32:33], v[32:33]
	v_pk_fma_f32 v[102:103], v[140:141], v[140:141], v[102:103]
	v_mov_b32_e32 v158, v104
	v_pk_fma_f32 v[102:103], v[142:143], v[142:143], v[102:103]
	v_pk_mul_f32 v[106:107], v[34:35], v[34:35]
	v_pk_fma_f32 v[102:103], v[144:145], v[144:145], v[102:103]
	v_mov_b32_e32 v154, v105
	v_pk_fma_f32 v[102:103], v[146:147], v[146:147], v[102:103]
	v_mov_b32_e32 v160, v106
	v_pk_fma_f32 v[102:103], v[152:153], v[152:153], v[102:103]
	v_mov_b32_e32 v156, v107
	v_pk_add_f32 v[102:103], v[158:159], v[102:103]
	s_nop 0
	v_pk_add_f32 v[102:103], v[154:155], v[102:103]
	s_nop 0
	v_pk_add_f32 v[102:103], v[160:161], v[102:103]
	s_nop 0
	v_pk_add_f32 v[102:103], v[156:157], v[102:103]
	ds_bpermute_b32 v105, v131, v103
	ds_bpermute_b32 v104, v131, v102
	s_waitcnt lgkmcnt(0)
	v_pk_add_f32 v[102:103], v[102:103], v[104:105]
	ds_bpermute_b32 v105, v132, v103
	ds_bpermute_b32 v104, v132, v102
	s_waitcnt lgkmcnt(0)
	v_pk_add_f32 v[102:103], v[102:103], v[104:105]
	ds_bpermute_b32 v105, v133, v103
	ds_bpermute_b32 v104, v133, v102
	s_waitcnt lgkmcnt(0)
	v_pk_add_f32 v[102:103], v[102:103], v[104:105]
	ds_bpermute_b32 v105, v134, v103
	ds_bpermute_b32 v104, v134, v102
	s_waitcnt lgkmcnt(0)
	v_pk_add_f32 v[102:103], v[102:103], v[104:105]
	ds_bpermute_b32 v105, v135, v103
	ds_bpermute_b32 v104, v135, v102
	s_waitcnt lgkmcnt(0)
	v_pk_add_f32 v[102:103], v[102:103], v[104:105]
	ds_bpermute_b32 v105, v136, v103
	ds_bpermute_b32 v104, v136, v102
	s_waitcnt lgkmcnt(0)
	v_pk_add_f32 v[102:103], v[102:103], v[104:105]
	s_nop 0
	v_pk_fma_f32 v[102:103], v[102:103], s[14:15], v[66:67] op_sel_hi:[1,0,0]
	s_nop 0
	v_mul_f32_e32 v104, 0x4b800000, v103
	v_cmp_gt_f32_e32 vcc, s25, v103
	s_nop 1
	v_cndmask_b32_e32 v103, v103, v104, vcc
	v_rsq_f32_e32 v103, v103
	s_nop 0
	v_mul_f32_e32 v104, 0x45800000, v103
	v_cndmask_b32_e32 v104, v103, v104, vcc
	v_pk_mul_f32 v[56:57], v[56:57], v[104:105] op_sel_hi:[1,0]
	v_pk_mul_f32 v[58:59], v[58:59], v[104:105] op_sel_hi:[1,0]
	v_pk_mul_f32 v[52:53], v[52:53], v[104:105] op_sel_hi:[1,0]
	v_pk_mul_f32 v[54:55], v[54:55], v[104:105] op_sel_hi:[1,0]
	v_pk_mul_f32 v[48:49], v[48:49], v[104:105] op_sel_hi:[1,0]
	v_pk_mul_f32 v[56:57], v[98:99], v[56:57]
	v_pk_mul_f32 v[58:59], v[100:101], v[58:59]
	v_pk_fma_f32 v[56:57], v[76:77], v[56:57], v[16:17]
	v_pk_fma_f32 v[58:59], v[78:79], v[58:59], v[18:19]
	v_cvt_pk_bf16_f32 v56, v56, v57
	v_cvt_pk_bf16_f32 v57, v58, v59
	global_store_dwordx2 v[108:109], v[56:57], off
	v_mov_b32_e32 v56, v220
	v_mov_b32_e32 v57, v221
	v_mov_b32_e32 v58, v222
	v_mov_b32_e32 v59, v223
	v_pk_mul_f32 v[50:51], v[50:51], v[104:105] op_sel_hi:[1,0]
	v_cmp_gt_f32_e32 vcc, s25, v102
	v_pk_mul_f32 v[52:53], v[56:57], v[52:53]
	v_pk_mul_f32 v[54:55], v[58:59], v[54:55]
	v_pk_fma_f32 v[52:53], v[52:53], v[80:81], v[20:21]
	v_pk_fma_f32 v[54:55], v[54:55], v[82:83], v[22:23]
	v_cvt_pk_bf16_f32 v52, v52, v53
	v_cvt_pk_bf16_f32 v53, v54, v55
	global_store_dwordx2 v[108:109], v[52:53], off offset:512
	v_mov_b32_e32 v52, v224
	v_mov_b32_e32 v53, v225
	v_mov_b32_e32 v54, v226
	v_mov_b32_e32 v55, v227
	v_pk_mul_f32 v[56:57], v[60:61], v[104:105] op_sel_hi:[1,0]
	v_pk_mul_f32 v[58:59], v[62:63], v[104:105] op_sel_hi:[1,0]
	v_pk_mul_f32 v[52:53], v[56:57], v[52:53]
	v_pk_mul_f32 v[54:55], v[58:59], v[54:55]
	v_pk_fma_f32 v[52:53], v[52:53], v[84:85], v[24:25]
	v_pk_fma_f32 v[54:55], v[54:55], v[86:87], v[26:27]
	v_cvt_pk_bf16_f32 v52, v52, v53
	v_cvt_pk_bf16_f32 v53, v54, v55
	global_store_dwordx2 v[108:109], v[52:53], off offset:1024
	v_mov_b32_e32 v52, v228
	v_mov_b32_e32 v53, v229
	v_mov_b32_e32 v54, v230
	v_mov_b32_e32 v55, v231
	v_pk_mul_f32 v[48:49], v[48:49], v[52:53]
	v_pk_mul_f32 v[50:51], v[50:51], v[54:55]
	v_pk_fma_f32 v[48:49], v[48:49], v[88:89], v[28:29]
	v_pk_fma_f32 v[50:51], v[50:51], v[90:91], v[30:31]
	v_cvt_pk_bf16_f32 v48, v48, v49
	v_cvt_pk_bf16_f32 v49, v50, v51
	global_store_dwordx2 v[108:109], v[48:49], off offset:1536
	v_mov_b32_e32 v48, v216
	v_mov_b32_e32 v49, v217
	v_mov_b32_e32 v50, v218
	v_mov_b32_e32 v51, v219
	v_mul_f32_e32 v54, 0x4b800000, v102
	v_cndmask_b32_e32 v54, v102, v54, vcc
	v_rsq_f32_e32 v54, v54
	v_lshl_add_u64 v[52:53], v[94:95], 0, v[96:97]
	v_mul_f32_e32 v55, 0x45800000, v54
	v_cndmask_b32_e32 v54, v54, v55, vcc
	v_pk_mul_f32 v[44:45], v[44:45], v[54:55] op_sel_hi:[1,0]
	v_pk_mul_f32 v[46:47], v[46:47], v[54:55] op_sel_hi:[1,0]
	v_pk_mul_f32 v[40:41], v[40:41], v[54:55] op_sel_hi:[1,0]
	v_pk_mul_f32 v[42:43], v[42:43], v[54:55] op_sel_hi:[1,0]
	v_pk_mul_f32 v[36:37], v[36:37], v[54:55] op_sel_hi:[1,0]
	v_pk_mul_f32 v[38:39], v[38:39], v[54:55] op_sel_hi:[1,0]
	v_pk_mul_f32 v[32:33], v[32:33], v[54:55] op_sel_hi:[1,0]
	v_pk_mul_f32 v[34:35], v[34:35], v[54:55] op_sel_hi:[1,0]
	v_pk_mul_f32 v[44:45], v[44:45], v[48:49]
	v_pk_mul_f32 v[46:47], v[46:47], v[50:51]
	v_pk_fma_f32 v[44:45], v[76:77], v[44:45], v[16:17]
	v_pk_fma_f32 v[46:47], v[78:79], v[46:47], v[18:19]
	v_cvt_pk_bf16_f32 v44, v44, v45
	v_cvt_pk_bf16_f32 v45, v46, v47
	global_store_dwordx2 v[52:53], v[44:45], off
	v_mov_b32_e32 v44, v220
	v_mov_b32_e32 v45, v221
	v_mov_b32_e32 v46, v222
	v_mov_b32_e32 v47, v223
	v_pk_mul_f32 v[40:41], v[40:41], v[44:45]
	v_pk_mul_f32 v[42:43], v[42:43], v[46:47]
	v_pk_fma_f32 v[40:41], v[80:81], v[40:41], v[20:21]
	v_pk_fma_f32 v[42:43], v[82:83], v[42:43], v[22:23]
	v_cvt_pk_bf16_f32 v40, v40, v41
	v_cvt_pk_bf16_f32 v41, v42, v43
	global_store_dwordx2 v[52:53], v[40:41], off offset:512
	v_mov_b32_e32 v40, v224
	v_mov_b32_e32 v41, v225
	v_mov_b32_e32 v42, v226
	v_mov_b32_e32 v43, v227
	v_pk_mul_f32 v[36:37], v[36:37], v[40:41]
	v_pk_mul_f32 v[38:39], v[38:39], v[42:43]
	v_pk_fma_f32 v[36:37], v[84:85], v[36:37], v[24:25]
	v_pk_fma_f32 v[38:39], v[86:87], v[38:39], v[26:27]
	v_cvt_pk_bf16_f32 v36, v36, v37
	v_cvt_pk_bf16_f32 v37, v38, v39
	global_store_dwordx2 v[52:53], v[36:37], off offset:1024
	v_mov_b32_e32 v36, v228
	v_mov_b32_e32 v37, v229
	v_mov_b32_e32 v38, v230
	v_mov_b32_e32 v39, v231
	v_pk_mul_f32 v[32:33], v[32:33], v[36:37]
	v_pk_mul_f32 v[34:35], v[34:35], v[38:39]
	v_pk_fma_f32 v[32:33], v[88:89], v[32:33], v[28:29]
	v_pk_fma_f32 v[34:35], v[90:91], v[34:35], v[30:31]
	v_cvt_pk_bf16_f32 v32, v32, v33
	v_cvt_pk_bf16_f32 v33, v34, v35
	global_store_dwordx2 v[52:53], v[32:33], off offset:1536
	s_cbranch_scc1 .LBB0_1264
	s_add_i32 s26, s26, s50
	s_add_i32 s3, s3, s15
	s_cmpk_gt_i32 s26, 0xff
	s_cbranch_scc0 .LBB0_1257
